# rwkv scan producer: chunk loads use scalar row bases stepped by SALU + one per-thread column offset; no 64-bit VALU address work beside the VALU-bound consumer
# speedup vs baseline: 1.0063x; 1.0063x over previous
; #define LDS_BARRIER() do { asm volatile("s_waitcnt lgkmcnt(0)" ::: "memory"); __builtin_amdgcn_s_barrier(); asm volatile("" ::: "memory"); } while (0)
; __device__ __forceinline__ void rwkv_load_chunk(RwkvRegs& R, int n, int pw, int b, int col, const bf16_t* RKV, const bf16_t* LO, const bf16_t* Y) {
; #pragma unroll
;     for (int i = 0; i < 8; ++i) { const int tt = pw + 4 * i, m = b * T_ + 32 * n + tt; const bf16_t* zr = RKV + (size_t)m * RKV_LD; const bf16_t* lo = LO + (size_t)m * 2048;
;         R.vr[i] = zr[col]; R.vx[i] = zr[512 + col]; R.vv[i] = zr[1024 + col]; R.ve[i] = lo[col]; R.va[i] = lo[512 + col]; R.vk[i] = Y[(size_t)m * D_ + col]; }
; }
; __device__ __forceinline__ void rwkv_scan(const Ctx& c, const Params& p, int o, int nblk) {
;     ...
;             for (int n = 0; n < 256; ++n) {
;                 LDS_BARRIER();
;                 if (n + 1 < 256) rwkv_write_chunk(L, R, n + 1, pw, c.lane);
;                 if (n + 2 < 256) rwkv_load_chunk(R, n + 2, pw, b, col, RKV, LO, Y);
;                 if (n >= 1) rwkv_store_chunk(L, n - 1, pw, c.lane, b, col, (bf16_t*)LO, half);
.LBB0_101:
	s_cmpk_gt_u32 s2, 0xfd
	s_cbranch_scc1 .LBB0_103
	s_add_i32 s11, s59, s72
	s_add_i32 s2, s11, 60
	s_mul_i32 s18, s2, 0xc00
	s_add_u32 s18, s16, s18
	s_addc_u32 s19, s17, 0
	s_lshl_b32 s62, s2, 12
	s_add_u32 s62, s12, s62
	s_addc_u32 s63, s13, 0
	s_lshl_b32 s2, s2, 11
	s_add_u32 s2, s74, s2
	s_addc_u32 s3, s75, 0
	s_waitcnt lgkmcnt(0)
	global_load_ushort v10, v2, s[18:19]
	global_load_ushort v11, v2, s[18:19] offset:1024
	global_load_ushort v12, v2, s[18:19] offset:2048
	global_load_ushort v13, v2, s[62:63]
	global_load_ushort v14, v2, s[62:63] offset:1024
	global_load_ushort v15, v2, s[2:3]
	s_add_u32 s18, s18, 0x3000
	s_addc_u32 s19, s19, 0
	s_add_u32 s62, s62, 0x4000
	s_addc_u32 s63, s63, 0
	s_add_u32 s2, s2, 0x2000
	s_addc_u32 s3, s3, 0
	global_load_ushort v16, v2, s[18:19]
	global_load_ushort v17, v2, s[18:19] offset:1024
	global_load_ushort v18, v2, s[18:19] offset:2048
	global_load_ushort v19, v2, s[62:63]
	global_load_ushort v20, v2, s[62:63] offset:1024
	global_load_ushort v21, v2, s[2:3]
	s_add_u32 s18, s18, 0x3000
	s_addc_u32 s19, s19, 0
	s_add_u32 s62, s62, 0x4000
	s_addc_u32 s63, s63, 0
	s_add_u32 s2, s2, 0x2000
	s_addc_u32 s3, s3, 0
	global_load_ushort v22, v2, s[18:19]
	global_load_ushort v23, v2, s[18:19] offset:1024
	global_load_ushort v24, v2, s[18:19] offset:2048
	global_load_ushort v25, v2, s[62:63]
	global_load_ushort v26, v2, s[62:63] offset:1024
	global_load_ushort v27, v2, s[2:3]
	s_add_u32 s18, s18, 0x3000
	s_addc_u32 s19, s19, 0
	s_add_u32 s62, s62, 0x4000
	s_addc_u32 s63, s63, 0
	s_add_u32 s2, s2, 0x2000
	s_addc_u32 s3, s3, 0
	global_load_ushort v28, v2, s[18:19]
	global_load_ushort v29, v2, s[18:19] offset:1024
	global_load_ushort v30, v2, s[18:19] offset:2048
	global_load_ushort v31, v2, s[62:63]
	global_load_ushort v32, v2, s[62:63] offset:1024
	global_load_ushort v33, v2, s[2:3]
	s_add_u32 s18, s18, 0x3000
	s_addc_u32 s19, s19, 0
	s_add_u32 s62, s62, 0x4000
	s_addc_u32 s63, s63, 0
	s_add_u32 s2, s2, 0x2000
	s_addc_u32 s3, s3, 0
	global_load_ushort v34, v2, s[18:19]
	global_load_ushort v35, v2, s[18:19] offset:1024
	global_load_ushort v36, v2, s[18:19] offset:2048
	global_load_ushort v37, v2, s[62:63]
	global_load_ushort v38, v2, s[62:63] offset:1024
	global_load_ushort v39, v2, s[2:3]
	s_add_u32 s18, s18, 0x3000
	s_addc_u32 s19, s19, 0
	s_add_u32 s62, s62, 0x4000
	s_addc_u32 s63, s63, 0
	s_add_u32 s2, s2, 0x2000
	s_addc_u32 s3, s3, 0
	global_load_ushort v40, v2, s[18:19]
	global_load_ushort v41, v2, s[18:19] offset:1024
	global_load_ushort v42, v2, s[18:19] offset:2048
	global_load_ushort v43, v2, s[62:63]
	global_load_ushort v44, v2, s[62:63] offset:1024
	global_load_ushort v45, v2, s[2:3]
	s_add_u32 s18, s18, 0x3000
	s_addc_u32 s19, s19, 0
	s_add_u32 s62, s62, 0x4000
	s_addc_u32 s63, s63, 0
	s_add_u32 s2, s2, 0x2000
	s_addc_u32 s3, s3, 0
	global_load_ushort v46, v2, s[18:19]
	global_load_ushort v47, v2, s[18:19] offset:1024
	global_load_ushort v48, v2, s[18:19] offset:2048
	global_load_ushort v49, v2, s[62:63]
	global_load_ushort v50, v2, s[62:63] offset:1024
	global_load_ushort v51, v2, s[2:3]
	s_add_u32 s18, s18, 0x3000
	s_addc_u32 s19, s19, 0
	s_add_u32 s62, s62, 0x4000
	s_addc_u32 s63, s63, 0
	s_add_u32 s2, s2, 0x2000
	s_addc_u32 s3, s3, 0
	global_load_ushort v52, v2, s[18:19]
	global_load_ushort v53, v2, s[18:19] offset:1024
	global_load_ushort v59, v2, s[18:19] offset:2048
	global_load_ushort v60, v2, s[62:63]
	global_load_ushort v61, v2, s[62:63] offset:1024
	global_load_ushort v62, v2, s[2:3]
